# XCD-local barriers at OUT, D2 and GU seams (write-through weight conversion + ready counter)
# speedup vs baseline: 1.0152x; 1.0152x over previous
; __device__ __forceinline__ unsigned cvt_pk_bf16(float lo, float hi) { unsigned r; asm volatile("v_cvt_pk_bf16_f32 %0, %1, %2" : "=v"(r) : "v"(lo), "v"(hi)); return r; }
; #define LAS __attribute__((address_space(3)))
; __device__ __forceinline__ void conv_finish(const ConvItem& c, const f32x4 (&v)[16], const float (&gs)[16], LAS float* scr, int lane) {
; #pragma unroll
;     for (int i = 0; i < 16; ++i) { const int kk = 4 * i + (lane >> 4); LAS float* d = scr + kk * 65 + 4 * (lane & 15);
;         d[0] = v[i][0] * gs[i]; d[1] = v[i][1] * gs[i]; d[2] = v[i][2] * gs[i]; d[3] = v[i][3] * gs[i]; }
;     asm volatile("s_waitcnt lgkmcnt(0)" ::: "memory");
;     const int cc = lane & 7;
; #pragma unroll
;     for (int j = 0; j < 8; ++j) { const int n = (lane >> 3) + 8 * j; const LAS float* sp = scr + (8 * cc) * 65 + n;
;         u32x4 o; o.x = cvt_pk_bf16(sp[0 * 65], sp[1 * 65]); o.y = cvt_pk_bf16(sp[2 * 65], sp[3 * 65]); o.z = cvt_pk_bf16(sp[4 * 65], sp[5 * 65]); o.w = cvt_pk_bf16(sp[6 * 65], sp[7 * 65]);
;         *(u32x4*)(c.dst + (size_t)n * c.K + 8 * cc) = o; }
;     asm volatile("s_waitcnt lgkmcnt(0)" ::: "memory");
.LBB0_297:
	s_waitcnt vmcnt(0)
	v_pk_mul_f32 v[184:185], v[2:3], v[134:135] op_sel_hi:[1,0]
	ds_write2_b32 v171, v184, v185 offset1:1
	v_pk_mul_f32 v[184:185], v[4:5], v[134:135] op_sel_hi:[1,0]
	ds_write2_b32 v171, v184, v185 offset0:2 offset1:3
	v_pk_mul_f32 v[184:185], v[6:7], v[132:133] op_sel_hi:[1,0]
	v_add_u32_e32 v181, 0x410, v171
	ds_write2_b32 v181, v184, v185 offset1:1
	v_pk_mul_f32 v[184:185], v[8:9], v[132:133] op_sel_hi:[1,0]
	v_add_u32_e32 v181, 0x418, v171
	ds_write2_b32 v181, v184, v185 offset1:1
	v_pk_mul_f32 v[184:185], v[10:11], v[138:139] op_sel_hi:[1,0]
	v_add_u32_e32 v181, 0x820, v171
	ds_write2_b32 v181, v184, v185 offset1:1
	v_pk_mul_f32 v[184:185], v[12:13], v[138:139] op_sel_hi:[1,0]
	v_add_u32_e32 v181, 0x828, v171
	ds_write2_b32 v181, v184, v185 offset1:1
	v_pk_mul_f32 v[184:185], v[14:15], v[136:137] op_sel_hi:[1,0]
	v_add_u32_e32 v181, 0xc30, v171
	ds_write2_b32 v181, v184, v185 offset1:1
	v_pk_mul_f32 v[184:185], v[16:17], v[136:137] op_sel_hi:[1,0]
	v_add_u32_e32 v181, 0xc38, v171
	ds_write2_b32 v181, v184, v185 offset1:1
	v_pk_mul_f32 v[184:185], v[18:19], v[142:143] op_sel_hi:[1,0]
	v_add_u32_e32 v181, 0x1040, v171
	ds_write2_b32 v181, v184, v185 offset1:1
	v_pk_mul_f32 v[184:185], v[20:21], v[142:143] op_sel_hi:[1,0]
	v_add_u32_e32 v181, 0x1048, v171
	ds_write2_b32 v181, v184, v185 offset1:1
	v_pk_mul_f32 v[184:185], v[22:23], v[140:141] op_sel_hi:[1,0]
	v_add_u32_e32 v181, 0x1450, v171
	ds_write2_b32 v181, v184, v185 offset1:1
	v_pk_mul_f32 v[184:185], v[24:25], v[140:141] op_sel_hi:[1,0]
	v_add_u32_e32 v181, 0x1458, v171
	ds_write2_b32 v181, v184, v185 offset1:1
	v_pk_mul_f32 v[184:185], v[26:27], v[146:147] op_sel_hi:[1,0]
	v_add_u32_e32 v181, 0x1860, v171
	ds_write2_b32 v181, v184, v185 offset1:1
	v_pk_mul_f32 v[184:185], v[28:29], v[146:147] op_sel_hi:[1,0]
	v_add_u32_e32 v181, 0x1868, v171
	ds_write2_b32 v181, v184, v185 offset1:1
	v_pk_mul_f32 v[184:185], v[30:31], v[144:145] op_sel_hi:[1,0]
	v_add_u32_e32 v181, 0x1c70, v171
	ds_write2_b32 v181, v184, v185 offset1:1
	v_pk_mul_f32 v[184:185], v[32:33], v[144:145] op_sel_hi:[1,0]
	v_add_u32_e32 v181, 0x1c78, v171
	ds_write2_b32 v181, v184, v185 offset1:1
	v_pk_mul_f32 v[184:185], v[34:35], v[150:151] op_sel_hi:[1,0]
	v_add_u32_e32 v181, 0x2080, v171
	ds_write2_b32 v181, v184, v185 offset1:1
	v_pk_mul_f32 v[184:185], v[36:37], v[150:151] op_sel_hi:[1,0]
	v_add_u32_e32 v181, 0x2088, v171
	ds_write2_b32 v181, v184, v185 offset1:1
	v_pk_mul_f32 v[184:185], v[38:39], v[148:149] op_sel_hi:[1,0]
	v_add_u32_e32 v181, 0x2490, v171
	ds_write2_b32 v181, v184, v185 offset1:1
	v_pk_mul_f32 v[184:185], v[40:41], v[148:149] op_sel_hi:[1,0]
	v_add_u32_e32 v181, 0x2498, v171
	ds_write2_b32 v181, v184, v185 offset1:1
	v_pk_mul_f32 v[184:185], v[42:43], v[154:155] op_sel_hi:[1,0]
	v_add_u32_e32 v181, 0x28a0, v171
	ds_write2_b32 v181, v184, v185 offset1:1
	v_pk_mul_f32 v[184:185], v[44:45], v[154:155] op_sel_hi:[1,0]
	v_add_u32_e32 v181, 0x28a8, v171
	ds_write2_b32 v181, v184, v185 offset1:1
	v_pk_mul_f32 v[184:185], v[46:47], v[152:153] op_sel_hi:[1,0]
	v_add_u32_e32 v181, 0x2cb0, v171
	ds_write2_b32 v181, v184, v185 offset1:1
	v_pk_mul_f32 v[184:185], v[48:49], v[152:153] op_sel_hi:[1,0]
	v_add_u32_e32 v181, 0x2cb8, v171
	ds_write2_b32 v181, v184, v185 offset1:1
	v_pk_mul_f32 v[184:185], v[50:51], v[158:159] op_sel_hi:[1,0]
	v_add_u32_e32 v181, 0x30c0, v171
	ds_write2_b32 v181, v184, v185 offset1:1
	v_pk_mul_f32 v[184:185], v[52:53], v[158:159] op_sel_hi:[1,0]
	v_add_u32_e32 v181, 0x30c8, v171
	ds_write2_b32 v181, v184, v185 offset1:1
	v_pk_mul_f32 v[184:185], v[54:55], v[156:157] op_sel_hi:[1,0]
	v_add_u32_e32 v181, 0x34d0, v171
	ds_write2_b32 v181, v184, v185 offset1:1
	v_pk_mul_f32 v[184:185], v[56:57], v[156:157] op_sel_hi:[1,0]
	v_add_u32_e32 v181, 0x34d8, v171
	ds_write2_b32 v181, v184, v185 offset1:1
	v_pk_mul_f32 v[184:185], v[58:59], v[162:163] op_sel_hi:[1,0]
	v_add_u32_e32 v181, 0x38e0, v171
	ds_write2_b32 v181, v184, v185 offset1:1
	v_pk_mul_f32 v[184:185], v[60:61], v[162:163] op_sel_hi:[1,0]
	v_add_u32_e32 v181, 0x38e8, v171
	ds_write2_b32 v181, v184, v185 offset1:1
	v_pk_mul_f32 v[184:185], v[62:63], v[160:161] op_sel_hi:[1,0]
	v_add_u32_e32 v181, 0x3cf0, v171
	ds_write2_b32 v181, v184, v185 offset1:1
	v_pk_mul_f32 v[184:185], v[64:65], v[160:161] op_sel_hi:[1,0]
	v_add_u32_e32 v181, 0x3cf8, v171
	ds_write2_b32 v181, v184, v185 offset1:1
	s_waitcnt lgkmcnt(0)
	v_mov_b32_e32 v181, v1
	ds_read2_b32 v[198:199], v169 offset1:65
	v_lshl_add_u64 v[184:185], v[130:131], 0, v[180:181]
	s_waitcnt lgkmcnt(0)
	v_cvt_pk_bf16_f32 v198, v198, v199
	ds_read2_b32 v[200:201], v169 offset0:130 offset1:195
	v_add_u32_e32 v181, 0x400, v169
	s_waitcnt lgkmcnt(0)
	v_cvt_pk_bf16_f32 v199, v200, v201
	ds_read2_b32 v[200:201], v181 offset0:4 offset1:69
	s_waitcnt lgkmcnt(0)
	v_cvt_pk_bf16_f32 v200, v200, v201
	ds_read2_b32 v[202:203], v181 offset0:134 offset1:199
	s_waitcnt lgkmcnt(0)
	v_cvt_pk_bf16_f32 v201, v202, v203
	v_mad_u64_u32 v[202:203], s[4:5], s10, v164, 0
	v_lshl_add_u64 v[202:203], v[202:203], 1, v[184:185]
	global_store_dwordx4 v[202:203], v[198:201], off sc1
	ds_read2_b32 v[198:199], v169 offset0:8 offset1:73
	s_andn2_b64 vcc, exec, s[30:31]
	s_waitcnt lgkmcnt(0)
	v_cvt_pk_bf16_f32 v198, v198, v199
	ds_read2_b32 v[200:201], v169 offset0:138 offset1:203
	s_waitcnt lgkmcnt(0)
	v_cvt_pk_bf16_f32 v199, v200, v201
	ds_read2_b32 v[200:201], v181 offset0:12 offset1:77
	s_waitcnt lgkmcnt(0)
	v_cvt_pk_bf16_f32 v200, v200, v201
	ds_read2_b32 v[202:203], v181 offset0:142 offset1:207
	s_waitcnt lgkmcnt(0)
; __device__ __forceinline__ unsigned cvt_pk_bf16(float lo, float hi) { unsigned r; asm volatile("v_cvt_pk_bf16_f32 %0, %1, %2" : "=v"(r) : "v"(lo), "v"(hi)); return r; }
; #define LAS __attribute__((address_space(3)))
; __device__ __forceinline__ void conv_finish(const ConvItem& c, const f32x4 (&v)[16], const float (&gs)[16], LAS float* scr, int lane) {
;     ...
;     for (int j = 0; j < 8; ++j) { const int n = (lane >> 3) + 8 * j; const LAS float* sp = scr + (8 * cc) * 65 + n;
;         u32x4 o; o.x = cvt_pk_bf16(sp[0 * 65], sp[1 * 65]); o.y = cvt_pk_bf16(sp[2 * 65], sp[3 * 65]); o.z = cvt_pk_bf16(sp[4 * 65], sp[5 * 65]); o.w = cvt_pk_bf16(sp[6 * 65], sp[7 * 65]);
;         *(u32x4*)(c.dst + (size_t)n * c.K + 8 * cc) = o; }
;     asm volatile("s_waitcnt lgkmcnt(0)" ::: "memory");
; }
; __device__ __forceinline__ void convert_weights(const Args& a, LAS unsigned char* lds, int l, int it_lo, int it_hi, int w, int NW, int wave, int lane) {
;     LAS float* scr = (LAS float*)(lds + wave * 16640);
;     int it = it_lo + w; if (it >= it_hi) return;
;     ConvItem cur = conv_decode(a, l, it); f32x4 v[16]; float gs[16];
;     conv_issue(cur, v, gs, lane);
; #pragma unroll 1
;     for (;;) {
;         const int nx = it + NW; const bool more = nx < it_hi;
;         ConvItem nxt = cur; f32x4 v2[16]; float gs2[16];
;         if (more) { nxt = conv_decode(a, l, nx); conv_issue(nxt, v2, gs2, lane); }
;         __builtin_amdgcn_sched_barrier(0);
;         conv_finish(cur, v, gs, scr, lane);
;         if (!more) break;
;         cur = nxt; it = nx;
; #pragma unroll
;         for (int i = 0; i < 16; ++i) { v[i] = v2[i]; gs[i] = gs2[i]; }
;     }
	v_cvt_pk_bf16_f32 v201, v202, v203
	v_mad_u64_u32 v[202:203], s[4:5], s10, v166, 0
	v_lshl_add_u64 v[202:203], v[202:203], 1, v[184:185]
	global_store_dwordx4 v[202:203], v[198:201], off sc1
	ds_read2_b32 v[198:199], v169 offset0:16 offset1:81
	s_waitcnt lgkmcnt(0)
	v_cvt_pk_bf16_f32 v198, v198, v199
	ds_read2_b32 v[200:201], v169 offset0:146 offset1:211
	s_waitcnt lgkmcnt(0)
	v_cvt_pk_bf16_f32 v199, v200, v201
	ds_read2_b32 v[200:201], v181 offset0:20 offset1:85
	s_waitcnt lgkmcnt(0)
	v_cvt_pk_bf16_f32 v200, v200, v201
	ds_read2_b32 v[202:203], v181 offset0:150 offset1:215
	s_waitcnt lgkmcnt(0)
	v_cvt_pk_bf16_f32 v201, v202, v203
	v_mad_u64_u32 v[202:203], s[4:5], s10, v168, 0
	v_lshl_add_u64 v[202:203], v[202:203], 1, v[184:185]
	global_store_dwordx4 v[202:203], v[198:201], off sc1
	ds_read2_b32 v[198:199], v169 offset0:24 offset1:89
	s_waitcnt lgkmcnt(0)
	v_cvt_pk_bf16_f32 v198, v198, v199
	ds_read2_b32 v[200:201], v169 offset0:154 offset1:219
	s_waitcnt lgkmcnt(0)
	v_cvt_pk_bf16_f32 v199, v200, v201
	ds_read2_b32 v[200:201], v181 offset0:28 offset1:93
	s_waitcnt lgkmcnt(0)
	v_cvt_pk_bf16_f32 v200, v200, v201
	ds_read2_b32 v[202:203], v181 offset0:158 offset1:223
	s_waitcnt lgkmcnt(0)
	v_cvt_pk_bf16_f32 v201, v202, v203
	v_mad_u64_u32 v[202:203], s[4:5], s10, v170, 0
	v_lshl_add_u64 v[202:203], v[202:203], 1, v[184:185]
	global_store_dwordx4 v[202:203], v[198:201], off sc1
	ds_read2_b32 v[198:199], v169 offset0:32 offset1:97
	s_waitcnt lgkmcnt(0)
	v_cvt_pk_bf16_f32 v198, v198, v199
	ds_read2_b32 v[200:201], v169 offset0:162 offset1:227
	s_waitcnt lgkmcnt(0)
	v_cvt_pk_bf16_f32 v199, v200, v201
	ds_read2_b32 v[200:201], v181 offset0:36 offset1:101
	s_waitcnt lgkmcnt(0)
	v_cvt_pk_bf16_f32 v200, v200, v201
	ds_read2_b32 v[202:203], v181 offset0:166 offset1:231
	s_waitcnt lgkmcnt(0)
	v_cvt_pk_bf16_f32 v201, v202, v203
	v_mad_u64_u32 v[202:203], s[4:5], s10, v172, 0
	v_lshl_add_u64 v[202:203], v[202:203], 1, v[184:185]
	global_store_dwordx4 v[202:203], v[198:201], off sc1
	ds_read2_b32 v[198:199], v169 offset0:40 offset1:105
	s_waitcnt lgkmcnt(0)
	v_cvt_pk_bf16_f32 v198, v198, v199
	ds_read2_b32 v[200:201], v169 offset0:170 offset1:235
	s_waitcnt lgkmcnt(0)
	v_cvt_pk_bf16_f32 v199, v200, v201
	ds_read2_b32 v[200:201], v181 offset0:44 offset1:109
	s_waitcnt lgkmcnt(0)
	v_cvt_pk_bf16_f32 v200, v200, v201
	ds_read2_b32 v[202:203], v181 offset0:174 offset1:239
	s_waitcnt lgkmcnt(0)
	v_cvt_pk_bf16_f32 v201, v202, v203
	v_mad_u64_u32 v[202:203], s[4:5], s10, v174, 0
	v_lshl_add_u64 v[202:203], v[202:203], 1, v[184:185]
	global_store_dwordx4 v[202:203], v[198:201], off sc1
	ds_read2_b32 v[198:199], v169 offset0:48 offset1:113
	s_waitcnt lgkmcnt(0)
	v_cvt_pk_bf16_f32 v198, v198, v199
	ds_read2_b32 v[200:201], v169 offset0:178 offset1:243
	s_waitcnt lgkmcnt(0)
	v_cvt_pk_bf16_f32 v199, v200, v201
	ds_read2_b32 v[200:201], v181 offset0:52 offset1:117
	s_waitcnt lgkmcnt(0)
	v_cvt_pk_bf16_f32 v200, v200, v201
	ds_read2_b32 v[202:203], v181 offset0:182 offset1:247
	s_waitcnt lgkmcnt(0)
	v_cvt_pk_bf16_f32 v201, v202, v203
	v_mad_u64_u32 v[202:203], s[4:5], s10, v176, 0
	v_lshl_add_u64 v[202:203], v[202:203], 1, v[184:185]
	global_store_dwordx4 v[202:203], v[198:201], off sc1
	ds_read2_b32 v[198:199], v169 offset0:56 offset1:121
	s_waitcnt lgkmcnt(0)
	v_cvt_pk_bf16_f32 v198, v198, v199
	ds_read2_b32 v[200:201], v169 offset0:186 offset1:251
	s_waitcnt lgkmcnt(0)
	v_cvt_pk_bf16_f32 v199, v200, v201
	ds_read2_b32 v[200:201], v181 offset0:60 offset1:125
	s_waitcnt lgkmcnt(0)
	v_cvt_pk_bf16_f32 v200, v200, v201
	ds_read2_b32 v[202:203], v181 offset0:190 offset1:255
	s_waitcnt lgkmcnt(0)
	v_cvt_pk_bf16_f32 v201, v202, v203
	v_mad_u64_u32 v[202:203], s[4:5], s10, v178, 0
	v_lshl_add_u64 v[184:185], v[202:203], 1, v[184:185]
	global_store_dwordx4 v[184:185], v[198:201], off sc1
	s_waitcnt lgkmcnt(0)
	s_cbranch_vccnz .LBB0_262
	v_mov_b64_e32 v[62:63], v[126:127]
	v_mov_b64_e32 v[58:59], v[118:119]
	v_mov_b64_e32 v[54:55], v[122:123]
	v_mov_b64_e32 v[50:51], v[110:111]
	v_mov_b64_e32 v[46:47], v[114:115]
	v_mov_b64_e32 v[42:43], v[102:103]
	v_mov_b64_e32 v[38:39], v[106:107]
	v_mov_b64_e32 v[34:35], v[94:95]
	v_mov_b64_e32 v[30:31], v[98:99]
	v_mov_b64_e32 v[26:27], v[86:87]
	v_mov_b64_e32 v[22:23], v[90:91]
	v_mov_b64_e32 v[18:19], v[78:79]
	v_mov_b64_e32 v[14:15], v[82:83]
	v_mov_b64_e32 v[10:11], v[70:71]
	v_mov_b64_e32 v[6:7], v[74:75]
	v_mov_b64_e32 v[2:3], v[66:67]
	v_mov_b64_e32 v[64:65], v[128:129]
	v_mov_b64_e32 v[60:61], v[120:121]
	v_mov_b64_e32 v[56:57], v[124:125]
	v_mov_b64_e32 v[52:53], v[112:113]
	v_mov_b64_e32 v[48:49], v[116:117]
	v_mov_b64_e32 v[44:45], v[104:105]
	v_mov_b64_e32 v[40:41], v[108:109]
	v_mov_b64_e32 v[36:37], v[96:97]
	v_mov_b64_e32 v[32:33], v[100:101]
	v_mov_b64_e32 v[28:29], v[88:89]
	v_mov_b64_e32 v[24:25], v[92:93]
	v_mov_b64_e32 v[20:21], v[80:81]
	v_mov_b64_e32 v[16:17], v[84:85]
	v_mov_b64_e32 v[12:13], v[72:73]
	v_mov_b64_e32 v[8:9], v[76:77]
	v_mov_b64_e32 v[4:5], v[68:69]
	v_mov_b32_e32 v160, v197
	v_mov_b32_e32 v162, v194
	v_mov_b32_e32 v156, v196
	v_mov_b32_e32 v158, v195
	v_mov_b32_e32 v152, v193
	v_mov_b32_e32 v154, v190
	v_mov_b32_e32 v148, v192
	v_mov_b32_e32 v150, v191
	v_mov_b32_e32 v144, v189
	v_mov_b32_e32 v146, v186
	v_mov_b32_e32 v140, v188
	v_mov_b32_e32 v142, v187
	v_mov_b32_e32 v136, v179
	v_mov_b32_e32 v138, v173
	v_mov_b32_e32 v132, v177
	v_mov_b32_e32 v134, v175
	s_mov_b32 s10, s13
	v_mov_b64_e32 v[130:131], v[182:183]
	s_mov_b32 s8, s12
	s_branch .LBB0_262

; __device__ __forceinline__ unsigned cvt_pk_bf16(float lo, float hi) { unsigned r; asm volatile("v_cvt_pk_bf16_f32 %0, %1, %2" : "=v"(r) : "v"(lo), "v"(hi)); return r; }
; #define LAS __attribute__((address_space(3)))
; __device__ __forceinline__ void conv_finish(const ConvItem& c, const f32x4 (&v)[16], const float (&gs)[16], LAS float* scr, int lane) {
; #pragma unroll
;     for (int i = 0; i < 16; ++i) { const int kk = 4 * i + (lane >> 4); LAS float* d = scr + kk * 65 + 4 * (lane & 15);
;         d[0] = v[i][0] * gs[i]; d[1] = v[i][1] * gs[i]; d[2] = v[i][2] * gs[i]; d[3] = v[i][3] * gs[i]; }
;     asm volatile("s_waitcnt lgkmcnt(0)" ::: "memory");
;     const int cc = lane & 7;
; #pragma unroll
;     for (int j = 0; j < 8; ++j) { const int n = (lane >> 3) + 8 * j; const LAS float* sp = scr + (8 * cc) * 65 + n;
;         u32x4 o; o.x = cvt_pk_bf16(sp[0 * 65], sp[1 * 65]); o.y = cvt_pk_bf16(sp[2 * 65], sp[3 * 65]); o.z = cvt_pk_bf16(sp[4 * 65], sp[5 * 65]); o.w = cvt_pk_bf16(sp[6 * 65], sp[7 * 65]);
;         *(u32x4*)(c.dst + (size_t)n * c.K + 8 * cc) = o; }
;     asm volatile("s_waitcnt lgkmcnt(0)" ::: "memory");
.LBB0_373:
	s_waitcnt vmcnt(0)
	v_pk_mul_f32 v[184:185], v[2:3], v[134:135] op_sel_hi:[1,0]
	ds_write2_b32 v171, v184, v185 offset1:1
	v_pk_mul_f32 v[184:185], v[4:5], v[134:135] op_sel_hi:[1,0]
	ds_write2_b32 v171, v184, v185 offset0:2 offset1:3
	v_pk_mul_f32 v[184:185], v[6:7], v[132:133] op_sel_hi:[1,0]
	v_add_u32_e32 v181, 0x410, v171
	ds_write2_b32 v181, v184, v185 offset1:1
	v_pk_mul_f32 v[184:185], v[8:9], v[132:133] op_sel_hi:[1,0]
	v_add_u32_e32 v181, 0x418, v171
	ds_write2_b32 v181, v184, v185 offset1:1
	v_pk_mul_f32 v[184:185], v[10:11], v[138:139] op_sel_hi:[1,0]
	v_add_u32_e32 v181, 0x820, v171
	ds_write2_b32 v181, v184, v185 offset1:1
	v_pk_mul_f32 v[184:185], v[12:13], v[138:139] op_sel_hi:[1,0]
	v_add_u32_e32 v181, 0x828, v171
	ds_write2_b32 v181, v184, v185 offset1:1
	v_pk_mul_f32 v[184:185], v[14:15], v[136:137] op_sel_hi:[1,0]
	v_add_u32_e32 v181, 0xc30, v171
	ds_write2_b32 v181, v184, v185 offset1:1
	v_pk_mul_f32 v[184:185], v[16:17], v[136:137] op_sel_hi:[1,0]
	v_add_u32_e32 v181, 0xc38, v171
	ds_write2_b32 v181, v184, v185 offset1:1
	v_pk_mul_f32 v[184:185], v[18:19], v[142:143] op_sel_hi:[1,0]
	v_add_u32_e32 v181, 0x1040, v171
	ds_write2_b32 v181, v184, v185 offset1:1
	v_pk_mul_f32 v[184:185], v[20:21], v[142:143] op_sel_hi:[1,0]
	v_add_u32_e32 v181, 0x1048, v171
	ds_write2_b32 v181, v184, v185 offset1:1
	v_pk_mul_f32 v[184:185], v[22:23], v[140:141] op_sel_hi:[1,0]
	v_add_u32_e32 v181, 0x1450, v171
	ds_write2_b32 v181, v184, v185 offset1:1
	v_pk_mul_f32 v[184:185], v[24:25], v[140:141] op_sel_hi:[1,0]
	v_add_u32_e32 v181, 0x1458, v171
	ds_write2_b32 v181, v184, v185 offset1:1
	v_pk_mul_f32 v[184:185], v[26:27], v[146:147] op_sel_hi:[1,0]
	v_add_u32_e32 v181, 0x1860, v171
	ds_write2_b32 v181, v184, v185 offset1:1
	v_pk_mul_f32 v[184:185], v[28:29], v[146:147] op_sel_hi:[1,0]
	v_add_u32_e32 v181, 0x1868, v171
	ds_write2_b32 v181, v184, v185 offset1:1
	v_pk_mul_f32 v[184:185], v[30:31], v[144:145] op_sel_hi:[1,0]
	v_add_u32_e32 v181, 0x1c70, v171
	ds_write2_b32 v181, v184, v185 offset1:1
	v_pk_mul_f32 v[184:185], v[32:33], v[144:145] op_sel_hi:[1,0]
	v_add_u32_e32 v181, 0x1c78, v171
	ds_write2_b32 v181, v184, v185 offset1:1
	v_pk_mul_f32 v[184:185], v[34:35], v[150:151] op_sel_hi:[1,0]
	v_add_u32_e32 v181, 0x2080, v171
	ds_write2_b32 v181, v184, v185 offset1:1
	v_pk_mul_f32 v[184:185], v[36:37], v[150:151] op_sel_hi:[1,0]
	v_add_u32_e32 v181, 0x2088, v171
	ds_write2_b32 v181, v184, v185 offset1:1
	v_pk_mul_f32 v[184:185], v[38:39], v[148:149] op_sel_hi:[1,0]
	v_add_u32_e32 v181, 0x2490, v171
	ds_write2_b32 v181, v184, v185 offset1:1
	v_pk_mul_f32 v[184:185], v[40:41], v[148:149] op_sel_hi:[1,0]
	v_add_u32_e32 v181, 0x2498, v171
	ds_write2_b32 v181, v184, v185 offset1:1
	v_pk_mul_f32 v[184:185], v[42:43], v[154:155] op_sel_hi:[1,0]
	v_add_u32_e32 v181, 0x28a0, v171
	ds_write2_b32 v181, v184, v185 offset1:1
	v_pk_mul_f32 v[184:185], v[44:45], v[154:155] op_sel_hi:[1,0]
	v_add_u32_e32 v181, 0x28a8, v171
	ds_write2_b32 v181, v184, v185 offset1:1
	v_pk_mul_f32 v[184:185], v[46:47], v[152:153] op_sel_hi:[1,0]
	v_add_u32_e32 v181, 0x2cb0, v171
	ds_write2_b32 v181, v184, v185 offset1:1
	v_pk_mul_f32 v[184:185], v[48:49], v[152:153] op_sel_hi:[1,0]
	v_add_u32_e32 v181, 0x2cb8, v171
	ds_write2_b32 v181, v184, v185 offset1:1
	v_pk_mul_f32 v[184:185], v[50:51], v[158:159] op_sel_hi:[1,0]
	v_add_u32_e32 v181, 0x30c0, v171
	ds_write2_b32 v181, v184, v185 offset1:1
	v_pk_mul_f32 v[184:185], v[52:53], v[158:159] op_sel_hi:[1,0]
	v_add_u32_e32 v181, 0x30c8, v171
	ds_write2_b32 v181, v184, v185 offset1:1
	v_pk_mul_f32 v[184:185], v[54:55], v[156:157] op_sel_hi:[1,0]
	v_add_u32_e32 v181, 0x34d0, v171
	ds_write2_b32 v181, v184, v185 offset1:1
	v_pk_mul_f32 v[184:185], v[56:57], v[156:157] op_sel_hi:[1,0]
	v_add_u32_e32 v181, 0x34d8, v171
	ds_write2_b32 v181, v184, v185 offset1:1
	v_pk_mul_f32 v[184:185], v[58:59], v[162:163] op_sel_hi:[1,0]
	v_add_u32_e32 v181, 0x38e0, v171
	ds_write2_b32 v181, v184, v185 offset1:1
	v_pk_mul_f32 v[184:185], v[60:61], v[162:163] op_sel_hi:[1,0]
	v_add_u32_e32 v181, 0x38e8, v171
	ds_write2_b32 v181, v184, v185 offset1:1
	v_pk_mul_f32 v[184:185], v[62:63], v[160:161] op_sel_hi:[1,0]
	v_add_u32_e32 v181, 0x3cf0, v171
	ds_write2_b32 v181, v184, v185 offset1:1
	v_pk_mul_f32 v[184:185], v[64:65], v[160:161] op_sel_hi:[1,0]
	v_add_u32_e32 v181, 0x3cf8, v171
	ds_write2_b32 v181, v184, v185 offset1:1
	s_waitcnt lgkmcnt(0)
	v_mov_b32_e32 v181, v1
	ds_read2_b32 v[198:199], v169 offset1:65
	v_lshl_add_u64 v[184:185], v[130:131], 0, v[180:181]
	s_waitcnt lgkmcnt(0)
	v_cvt_pk_bf16_f32 v198, v198, v199
	ds_read2_b32 v[200:201], v169 offset0:130 offset1:195
	v_add_u32_e32 v181, 0x400, v169
	s_waitcnt lgkmcnt(0)
	v_cvt_pk_bf16_f32 v199, v200, v201
	ds_read2_b32 v[200:201], v181 offset0:4 offset1:69
	s_waitcnt lgkmcnt(0)
	v_cvt_pk_bf16_f32 v200, v200, v201
	ds_read2_b32 v[202:203], v181 offset0:134 offset1:199
	s_waitcnt lgkmcnt(0)
	v_cvt_pk_bf16_f32 v201, v202, v203
	v_mad_u64_u32 v[202:203], s[4:5], s14, v164, 0
	v_lshl_add_u64 v[202:203], v[202:203], 1, v[184:185]
	global_store_dwordx4 v[202:203], v[198:201], off sc1
	ds_read2_b32 v[198:199], v169 offset0:8 offset1:73
	s_andn2_b64 vcc, exec, s[46:47]
	s_waitcnt lgkmcnt(0)
	v_cvt_pk_bf16_f32 v198, v198, v199
	ds_read2_b32 v[200:201], v169 offset0:138 offset1:203
	s_waitcnt lgkmcnt(0)
	v_cvt_pk_bf16_f32 v199, v200, v201
	ds_read2_b32 v[200:201], v181 offset0:12 offset1:77
	s_waitcnt lgkmcnt(0)
	v_cvt_pk_bf16_f32 v200, v200, v201
	ds_read2_b32 v[202:203], v181 offset0:142 offset1:207
	s_waitcnt lgkmcnt(0)
; __device__ __forceinline__ unsigned cvt_pk_bf16(float lo, float hi) { unsigned r; asm volatile("v_cvt_pk_bf16_f32 %0, %1, %2" : "=v"(r) : "v"(lo), "v"(hi)); return r; }
; #define LAS __attribute__((address_space(3)))
; __device__ __forceinline__ void conv_finish(const ConvItem& c, const f32x4 (&v)[16], const float (&gs)[16], LAS float* scr, int lane) {
;     ...
;     for (int j = 0; j < 8; ++j) { const int n = (lane >> 3) + 8 * j; const LAS float* sp = scr + (8 * cc) * 65 + n;
;         u32x4 o; o.x = cvt_pk_bf16(sp[0 * 65], sp[1 * 65]); o.y = cvt_pk_bf16(sp[2 * 65], sp[3 * 65]); o.z = cvt_pk_bf16(sp[4 * 65], sp[5 * 65]); o.w = cvt_pk_bf16(sp[6 * 65], sp[7 * 65]);
;         *(u32x4*)(c.dst + (size_t)n * c.K + 8 * cc) = o; }
;     asm volatile("s_waitcnt lgkmcnt(0)" ::: "memory");
; }
; __device__ __forceinline__ void convert_weights(const Args& a, LAS unsigned char* lds, int l, int it_lo, int it_hi, int w, int NW, int wave, int lane) {
;     LAS float* scr = (LAS float*)(lds + wave * 16640);
;     int it = it_lo + w; if (it >= it_hi) return;
;     ConvItem cur = conv_decode(a, l, it); f32x4 v[16]; float gs[16];
;     conv_issue(cur, v, gs, lane);
; #pragma unroll 1
;     for (;;) {
;         const int nx = it + NW; const bool more = nx < it_hi;
;         ConvItem nxt = cur; f32x4 v2[16]; float gs2[16];
;         if (more) { nxt = conv_decode(a, l, nx); conv_issue(nxt, v2, gs2, lane); }
;         __builtin_amdgcn_sched_barrier(0);
;         conv_finish(cur, v, gs, scr, lane);
;         if (!more) break;
;         cur = nxt; it = nx;
; #pragma unroll
;         for (int i = 0; i < 16; ++i) { v[i] = v2[i]; gs[i] = gs2[i]; }
;     }
	v_cvt_pk_bf16_f32 v201, v202, v203
	v_mad_u64_u32 v[202:203], s[4:5], s14, v166, 0
	v_lshl_add_u64 v[202:203], v[202:203], 1, v[184:185]
	global_store_dwordx4 v[202:203], v[198:201], off sc1
	ds_read2_b32 v[198:199], v169 offset0:16 offset1:81
	s_waitcnt lgkmcnt(0)
	v_cvt_pk_bf16_f32 v198, v198, v199
	ds_read2_b32 v[200:201], v169 offset0:146 offset1:211
	s_waitcnt lgkmcnt(0)
	v_cvt_pk_bf16_f32 v199, v200, v201
	ds_read2_b32 v[200:201], v181 offset0:20 offset1:85
	s_waitcnt lgkmcnt(0)
	v_cvt_pk_bf16_f32 v200, v200, v201
	ds_read2_b32 v[202:203], v181 offset0:150 offset1:215
	s_waitcnt lgkmcnt(0)
	v_cvt_pk_bf16_f32 v201, v202, v203
	v_mad_u64_u32 v[202:203], s[4:5], s14, v168, 0
	v_lshl_add_u64 v[202:203], v[202:203], 1, v[184:185]
	global_store_dwordx4 v[202:203], v[198:201], off sc1
	ds_read2_b32 v[198:199], v169 offset0:24 offset1:89
	s_waitcnt lgkmcnt(0)
	v_cvt_pk_bf16_f32 v198, v198, v199
	ds_read2_b32 v[200:201], v169 offset0:154 offset1:219
	s_waitcnt lgkmcnt(0)
	v_cvt_pk_bf16_f32 v199, v200, v201
	ds_read2_b32 v[200:201], v181 offset0:28 offset1:93
	s_waitcnt lgkmcnt(0)
	v_cvt_pk_bf16_f32 v200, v200, v201
	ds_read2_b32 v[202:203], v181 offset0:158 offset1:223
	s_waitcnt lgkmcnt(0)
	v_cvt_pk_bf16_f32 v201, v202, v203
	v_mad_u64_u32 v[202:203], s[4:5], s14, v170, 0
	v_lshl_add_u64 v[202:203], v[202:203], 1, v[184:185]
	global_store_dwordx4 v[202:203], v[198:201], off sc1
	ds_read2_b32 v[198:199], v169 offset0:32 offset1:97
	s_waitcnt lgkmcnt(0)
	v_cvt_pk_bf16_f32 v198, v198, v199
	ds_read2_b32 v[200:201], v169 offset0:162 offset1:227
	s_waitcnt lgkmcnt(0)
	v_cvt_pk_bf16_f32 v199, v200, v201
	ds_read2_b32 v[200:201], v181 offset0:36 offset1:101
	s_waitcnt lgkmcnt(0)
	v_cvt_pk_bf16_f32 v200, v200, v201
	ds_read2_b32 v[202:203], v181 offset0:166 offset1:231
	s_waitcnt lgkmcnt(0)
	v_cvt_pk_bf16_f32 v201, v202, v203
	v_mad_u64_u32 v[202:203], s[4:5], s14, v172, 0
	v_lshl_add_u64 v[202:203], v[202:203], 1, v[184:185]
	global_store_dwordx4 v[202:203], v[198:201], off sc1
	ds_read2_b32 v[198:199], v169 offset0:40 offset1:105
	s_waitcnt lgkmcnt(0)
	v_cvt_pk_bf16_f32 v198, v198, v199
	ds_read2_b32 v[200:201], v169 offset0:170 offset1:235
	s_waitcnt lgkmcnt(0)
	v_cvt_pk_bf16_f32 v199, v200, v201
	ds_read2_b32 v[200:201], v181 offset0:44 offset1:109
	s_waitcnt lgkmcnt(0)
	v_cvt_pk_bf16_f32 v200, v200, v201
	ds_read2_b32 v[202:203], v181 offset0:174 offset1:239
	s_waitcnt lgkmcnt(0)
	v_cvt_pk_bf16_f32 v201, v202, v203
	v_mad_u64_u32 v[202:203], s[4:5], s14, v174, 0
	v_lshl_add_u64 v[202:203], v[202:203], 1, v[184:185]
	global_store_dwordx4 v[202:203], v[198:201], off sc1
	ds_read2_b32 v[198:199], v169 offset0:48 offset1:113
	s_waitcnt lgkmcnt(0)
	v_cvt_pk_bf16_f32 v198, v198, v199
	ds_read2_b32 v[200:201], v169 offset0:178 offset1:243
	s_waitcnt lgkmcnt(0)
	v_cvt_pk_bf16_f32 v199, v200, v201
	ds_read2_b32 v[200:201], v181 offset0:52 offset1:117
	s_waitcnt lgkmcnt(0)
	v_cvt_pk_bf16_f32 v200, v200, v201
	ds_read2_b32 v[202:203], v181 offset0:182 offset1:247
	s_waitcnt lgkmcnt(0)
	v_cvt_pk_bf16_f32 v201, v202, v203
	v_mad_u64_u32 v[202:203], s[4:5], s14, v176, 0
	v_lshl_add_u64 v[202:203], v[202:203], 1, v[184:185]
	global_store_dwordx4 v[202:203], v[198:201], off sc1
	ds_read2_b32 v[198:199], v169 offset0:56 offset1:121
	s_waitcnt lgkmcnt(0)
	v_cvt_pk_bf16_f32 v198, v198, v199
	ds_read2_b32 v[200:201], v169 offset0:186 offset1:251
	s_waitcnt lgkmcnt(0)
	v_cvt_pk_bf16_f32 v199, v200, v201
	ds_read2_b32 v[200:201], v181 offset0:60 offset1:125
	s_waitcnt lgkmcnt(0)
	v_cvt_pk_bf16_f32 v200, v200, v201
	ds_read2_b32 v[202:203], v181 offset0:190 offset1:255
	s_waitcnt lgkmcnt(0)
	v_cvt_pk_bf16_f32 v201, v202, v203
	v_mad_u64_u32 v[202:203], s[4:5], s14, v178, 0
	v_lshl_add_u64 v[184:185], v[202:203], 1, v[184:185]
	global_store_dwordx4 v[184:185], v[198:201], off sc1
	s_waitcnt lgkmcnt(0)
	s_cbranch_vccnz .LBB0_344
	v_mov_b64_e32 v[62:63], v[126:127]
	v_mov_b64_e32 v[58:59], v[118:119]
	v_mov_b64_e32 v[54:55], v[122:123]
	v_mov_b64_e32 v[50:51], v[110:111]
	v_mov_b64_e32 v[46:47], v[114:115]
	v_mov_b64_e32 v[42:43], v[102:103]
	v_mov_b64_e32 v[38:39], v[106:107]
	v_mov_b64_e32 v[34:35], v[94:95]
	v_mov_b64_e32 v[30:31], v[98:99]
	v_mov_b64_e32 v[26:27], v[86:87]
	v_mov_b64_e32 v[22:23], v[90:91]
	v_mov_b64_e32 v[18:19], v[78:79]
	v_mov_b64_e32 v[14:15], v[82:83]
	v_mov_b64_e32 v[10:11], v[70:71]
	v_mov_b64_e32 v[6:7], v[74:75]
	v_mov_b64_e32 v[2:3], v[66:67]
	v_mov_b64_e32 v[64:65], v[128:129]
	v_mov_b64_e32 v[60:61], v[120:121]
	v_mov_b64_e32 v[56:57], v[124:125]
	v_mov_b64_e32 v[52:53], v[112:113]
	v_mov_b64_e32 v[48:49], v[116:117]
	v_mov_b64_e32 v[44:45], v[104:105]
	v_mov_b64_e32 v[40:41], v[108:109]
	v_mov_b64_e32 v[36:37], v[96:97]
	v_mov_b64_e32 v[32:33], v[100:101]
	v_mov_b64_e32 v[28:29], v[88:89]
	v_mov_b64_e32 v[24:25], v[92:93]
	v_mov_b64_e32 v[20:21], v[80:81]
	v_mov_b64_e32 v[16:17], v[84:85]
	v_mov_b64_e32 v[12:13], v[72:73]
	v_mov_b64_e32 v[8:9], v[76:77]
	v_mov_b64_e32 v[4:5], v[68:69]
	v_mov_b32_e32 v160, v197
	v_mov_b32_e32 v162, v194
	v_mov_b32_e32 v156, v196
	v_mov_b32_e32 v158, v195
	v_mov_b32_e32 v152, v193
	v_mov_b32_e32 v154, v190
	v_mov_b32_e32 v148, v192
	v_mov_b32_e32 v150, v191
	v_mov_b32_e32 v144, v189
	v_mov_b32_e32 v146, v186
	v_mov_b32_e32 v140, v188
	v_mov_b32_e32 v142, v187
	v_mov_b32_e32 v136, v179
	v_mov_b32_e32 v138, v173
	v_mov_b32_e32 v132, v177
	v_mov_b32_e32 v134, v175
	s_mov_b32 s14, s22
	v_mov_b64_e32 v[130:131], v[182:183]
	s_mov_b32 s13, s21
	s_branch .LBB0_344

; __device__ __forceinline__ unsigned cvt_pk_bf16(float lo, float hi) { unsigned r; asm volatile("v_cvt_pk_bf16_f32 %0, %1, %2" : "=v"(r) : "v"(lo), "v"(hi)); return r; }
; #define LAS __attribute__((address_space(3)))
; __device__ __forceinline__ void conv_finish(const ConvItem& c, const f32x4 (&v)[16], const float (&gs)[16], LAS float* scr, int lane) {
; #pragma unroll
;     for (int i = 0; i < 16; ++i) { const int kk = 4 * i + (lane >> 4); LAS float* d = scr + kk * 65 + 4 * (lane & 15);
;         d[0] = v[i][0] * gs[i]; d[1] = v[i][1] * gs[i]; d[2] = v[i][2] * gs[i]; d[3] = v[i][3] * gs[i]; }
;     asm volatile("s_waitcnt lgkmcnt(0)" ::: "memory");
;     const int cc = lane & 7;
; #pragma unroll
;     for (int j = 0; j < 8; ++j) { const int n = (lane >> 3) + 8 * j; const LAS float* sp = scr + (8 * cc) * 65 + n;
;         u32x4 o; o.x = cvt_pk_bf16(sp[0 * 65], sp[1 * 65]); o.y = cvt_pk_bf16(sp[2 * 65], sp[3 * 65]); o.z = cvt_pk_bf16(sp[4 * 65], sp[5 * 65]); o.w = cvt_pk_bf16(sp[6 * 65], sp[7 * 65]);
;         *(u32x4*)(c.dst + (size_t)n * c.K + 8 * cc) = o; }
;     asm volatile("s_waitcnt lgkmcnt(0)" ::: "memory");
.LBB0_384:
	s_waitcnt vmcnt(0)
	v_pk_mul_f32 v[226:227], v[2:3], v[130:131] op_sel_hi:[1,0]
	ds_write2_b32 v135, v226, v227 offset1:1
	v_pk_mul_f32 v[226:227], v[4:5], v[130:131] op_sel_hi:[1,0]
	ds_write2_b32 v135, v226, v227 offset0:2 offset1:3
	v_pk_mul_f32 v[226:227], v[10:11], v[132:133] op_sel_hi:[1,0]
	v_add_u32_e32 v165, 0x410, v135
	ds_write2_b32 v165, v226, v227 offset1:1
	v_pk_mul_f32 v[226:227], v[12:13], v[132:133] op_sel_hi:[1,0]
	v_add_u32_e32 v165, 0x418, v135
	ds_write2_b32 v165, v226, v227 offset1:1
	v_pk_mul_f32 v[226:227], v[6:7], v[134:135] op_sel_hi:[1,0]
	v_add_u32_e32 v165, 0x820, v135
	ds_write2_b32 v165, v226, v227 offset1:1
	v_pk_mul_f32 v[226:227], v[8:9], v[134:135] op_sel_hi:[1,0]
	v_add_u32_e32 v165, 0x828, v135
	ds_write2_b32 v165, v226, v227 offset1:1
	v_pk_mul_f32 v[226:227], v[18:19], v[136:137] op_sel_hi:[1,0]
	v_add_u32_e32 v165, 0xc30, v135
	ds_write2_b32 v165, v226, v227 offset1:1
	v_pk_mul_f32 v[226:227], v[20:21], v[136:137] op_sel_hi:[1,0]
	v_add_u32_e32 v165, 0xc38, v135
	ds_write2_b32 v165, v226, v227 offset1:1
	v_pk_mul_f32 v[226:227], v[14:15], v[138:139] op_sel_hi:[1,0]
	v_add_u32_e32 v165, 0x1040, v135
	ds_write2_b32 v165, v226, v227 offset1:1
	v_pk_mul_f32 v[226:227], v[16:17], v[138:139] op_sel_hi:[1,0]
	v_add_u32_e32 v165, 0x1048, v135
	ds_write2_b32 v165, v226, v227 offset1:1
	v_pk_mul_f32 v[226:227], v[26:27], v[140:141] op_sel_hi:[1,0]
	v_add_u32_e32 v165, 0x1450, v135
	ds_write2_b32 v165, v226, v227 offset1:1
	v_pk_mul_f32 v[226:227], v[28:29], v[140:141] op_sel_hi:[1,0]
	v_add_u32_e32 v165, 0x1458, v135
	ds_write2_b32 v165, v226, v227 offset1:1
	v_pk_mul_f32 v[226:227], v[22:23], v[142:143] op_sel_hi:[1,0]
	v_add_u32_e32 v165, 0x1860, v135
	ds_write2_b32 v165, v226, v227 offset1:1
	v_pk_mul_f32 v[226:227], v[24:25], v[142:143] op_sel_hi:[1,0]
	v_add_u32_e32 v165, 0x1868, v135
	ds_write2_b32 v165, v226, v227 offset1:1
	v_pk_mul_f32 v[226:227], v[34:35], v[144:145] op_sel_hi:[1,0]
	v_add_u32_e32 v165, 0x1c70, v135
	ds_write2_b32 v165, v226, v227 offset1:1
	v_pk_mul_f32 v[226:227], v[36:37], v[144:145] op_sel_hi:[1,0]
	v_add_u32_e32 v165, 0x1c78, v135
	ds_write2_b32 v165, v226, v227 offset1:1
	v_pk_mul_f32 v[226:227], v[30:31], v[146:147] op_sel_hi:[1,0]
	v_add_u32_e32 v165, 0x2080, v135
	ds_write2_b32 v165, v226, v227 offset1:1
	v_pk_mul_f32 v[226:227], v[32:33], v[146:147] op_sel_hi:[1,0]
	v_add_u32_e32 v165, 0x2088, v135
	ds_write2_b32 v165, v226, v227 offset1:1
	v_pk_mul_f32 v[226:227], v[42:43], v[148:149] op_sel_hi:[1,0]
	v_add_u32_e32 v165, 0x2490, v135
	ds_write2_b32 v165, v226, v227 offset1:1
	v_pk_mul_f32 v[226:227], v[44:45], v[148:149] op_sel_hi:[1,0]
	v_add_u32_e32 v165, 0x2498, v135
	ds_write2_b32 v165, v226, v227 offset1:1
	v_pk_mul_f32 v[226:227], v[38:39], v[150:151] op_sel_hi:[1,0]
	v_add_u32_e32 v165, 0x28a0, v135
	ds_write2_b32 v165, v226, v227 offset1:1
	v_pk_mul_f32 v[226:227], v[40:41], v[150:151] op_sel_hi:[1,0]
	v_add_u32_e32 v165, 0x28a8, v135
	ds_write2_b32 v165, v226, v227 offset1:1
	v_pk_mul_f32 v[226:227], v[50:51], v[152:153] op_sel_hi:[1,0]
	v_add_u32_e32 v165, 0x2cb0, v135
	ds_write2_b32 v165, v226, v227 offset1:1
	v_pk_mul_f32 v[226:227], v[52:53], v[152:153] op_sel_hi:[1,0]
	v_add_u32_e32 v165, 0x2cb8, v135
	ds_write2_b32 v165, v226, v227 offset1:1
	v_pk_mul_f32 v[226:227], v[46:47], v[154:155] op_sel_hi:[1,0]
	v_add_u32_e32 v165, 0x30c0, v135
	ds_write2_b32 v165, v226, v227 offset1:1
	v_pk_mul_f32 v[226:227], v[48:49], v[154:155] op_sel_hi:[1,0]
	v_add_u32_e32 v165, 0x30c8, v135
	ds_write2_b32 v165, v226, v227 offset1:1
	v_pk_mul_f32 v[226:227], v[58:59], v[156:157] op_sel_hi:[1,0]
	v_add_u32_e32 v165, 0x34d0, v135
	ds_write2_b32 v165, v226, v227 offset1:1
	v_pk_mul_f32 v[226:227], v[60:61], v[156:157] op_sel_hi:[1,0]
	v_add_u32_e32 v165, 0x34d8, v135
	ds_write2_b32 v165, v226, v227 offset1:1
	v_pk_mul_f32 v[226:227], v[54:55], v[158:159] op_sel_hi:[1,0]
	v_add_u32_e32 v165, 0x38e0, v135
	ds_write2_b32 v165, v226, v227 offset1:1
	v_pk_mul_f32 v[226:227], v[56:57], v[158:159] op_sel_hi:[1,0]
	v_add_u32_e32 v165, 0x38e8, v135
	ds_write2_b32 v165, v226, v227 offset1:1
	v_pk_mul_f32 v[226:227], v[62:63], v[160:161] op_sel_hi:[1,0]
	v_add_u32_e32 v165, 0x3cf0, v135
	ds_write2_b32 v165, v226, v227 offset1:1
	v_pk_mul_f32 v[226:227], v[64:65], v[160:161] op_sel_hi:[1,0]
	v_add_u32_e32 v165, 0x3cf8, v135
	ds_write2_b32 v165, v226, v227 offset1:1
	s_waitcnt lgkmcnt(0)
	ds_read2_b32 v[228:229], v131 offset1:65
	s_waitcnt lgkmcnt(0)
	v_cvt_pk_bf16_f32 v228, v228, v229
	ds_read2_b32 v[230:231], v131 offset0:130 offset1:195
	v_add_u32_e32 v165, 0x400, v131
	s_waitcnt lgkmcnt(0)
	v_cvt_pk_bf16_f32 v229, v230, v231
	ds_read2_b32 v[230:231], v165 offset0:4 offset1:69
	v_lshl_add_u64 v[226:227], s[28:29], 0, v[0:1]
	s_waitcnt lgkmcnt(0)
	v_cvt_pk_bf16_f32 v230, v230, v231
	ds_read2_b32 v[232:233], v165 offset0:134 offset1:199
	v_mov_b32_e32 v197, v1
	s_waitcnt lgkmcnt(0)
	v_cvt_pk_bf16_f32 v231, v232, v233
	v_lshl_add_u64 v[232:233], v[226:227], 0, v[196:197]
	global_store_dwordx4 v[232:233], v[228:231], off sc1
	ds_read2_b32 v[228:229], v131 offset0:8 offset1:73
	v_mov_b32_e32 v199, v1
	s_waitcnt lgkmcnt(0)
	v_cvt_pk_bf16_f32 v228, v228, v229
	ds_read2_b32 v[230:231], v131 offset0:138 offset1:203
	s_waitcnt lgkmcnt(0)
	v_cvt_pk_bf16_f32 v229, v230, v231
	ds_read2_b32 v[230:231], v165 offset0:12 offset1:77
	s_waitcnt lgkmcnt(0)
	v_cvt_pk_bf16_f32 v230, v230, v231
	ds_read2_b32 v[232:233], v165 offset0:142 offset1:207
	s_waitcnt lgkmcnt(0)
; __device__ __forceinline__ unsigned cvt_pk_bf16(float lo, float hi) { unsigned r; asm volatile("v_cvt_pk_bf16_f32 %0, %1, %2" : "=v"(r) : "v"(lo), "v"(hi)); return r; }
; #define LAS __attribute__((address_space(3)))
; __device__ __forceinline__ void conv_finish(const ConvItem& c, const f32x4 (&v)[16], const float (&gs)[16], LAS float* scr, int lane) {
;     ...
;     for (int j = 0; j < 8; ++j) { const int n = (lane >> 3) + 8 * j; const LAS float* sp = scr + (8 * cc) * 65 + n;
;         u32x4 o; o.x = cvt_pk_bf16(sp[0 * 65], sp[1 * 65]); o.y = cvt_pk_bf16(sp[2 * 65], sp[3 * 65]); o.z = cvt_pk_bf16(sp[4 * 65], sp[5 * 65]); o.w = cvt_pk_bf16(sp[6 * 65], sp[7 * 65]);
;         *(u32x4*)(c.dst + (size_t)n * c.K + 8 * cc) = o; }
;     asm volatile("s_waitcnt lgkmcnt(0)" ::: "memory");
; }
; __device__ __forceinline__ void convert_weights(const Args& a, LAS unsigned char* lds, int l, int it_lo, int it_hi, int w, int NW, int wave, int lane) {
;     LAS float* scr = (LAS float*)(lds + wave * 16640);
;     int it = it_lo + w; if (it >= it_hi) return;
;     ConvItem cur = conv_decode(a, l, it); f32x4 v[16]; float gs[16];
;     conv_issue(cur, v, gs, lane);
; #pragma unroll 1
;     for (;;) {
;         const int nx = it + NW; const bool more = nx < it_hi;
;         ConvItem nxt = cur; f32x4 v2[16]; float gs2[16];
;         if (more) { nxt = conv_decode(a, l, nx); conv_issue(nxt, v2, gs2, lane); }
;         __builtin_amdgcn_sched_barrier(0);
;         conv_finish(cur, v, gs, scr, lane);
;         if (!more) break;
;         cur = nxt; it = nx;
; #pragma unroll
;         for (int i = 0; i < 16; ++i) { v[i] = v2[i]; gs[i] = gs2[i]; }
;     }
	v_cvt_pk_bf16_f32 v231, v232, v233
	v_lshl_add_u64 v[232:233], v[226:227], 0, v[198:199]
	global_store_dwordx4 v[232:233], v[228:231], off sc1
	ds_read2_b32 v[228:229], v131 offset0:16 offset1:81
	v_mov_b32_e32 v201, v1
	s_waitcnt lgkmcnt(0)
	v_cvt_pk_bf16_f32 v228, v228, v229
	ds_read2_b32 v[230:231], v131 offset0:146 offset1:211
	s_waitcnt lgkmcnt(0)
	v_cvt_pk_bf16_f32 v229, v230, v231
	ds_read2_b32 v[230:231], v165 offset0:20 offset1:85
	s_waitcnt lgkmcnt(0)
	v_cvt_pk_bf16_f32 v230, v230, v231
	ds_read2_b32 v[232:233], v165 offset0:150 offset1:215
	s_waitcnt lgkmcnt(0)
	v_cvt_pk_bf16_f32 v231, v232, v233
	v_lshl_add_u64 v[232:233], v[226:227], 0, v[200:201]
	global_store_dwordx4 v[232:233], v[228:231], off sc1
	ds_read2_b32 v[228:229], v131 offset0:24 offset1:89
	v_mov_b32_e32 v203, v1
	s_waitcnt lgkmcnt(0)
	v_cvt_pk_bf16_f32 v228, v228, v229
	ds_read2_b32 v[230:231], v131 offset0:154 offset1:219
	s_waitcnt lgkmcnt(0)
	v_cvt_pk_bf16_f32 v229, v230, v231
	ds_read2_b32 v[230:231], v165 offset0:28 offset1:93
	s_waitcnt lgkmcnt(0)
	v_cvt_pk_bf16_f32 v230, v230, v231
	ds_read2_b32 v[232:233], v165 offset0:158 offset1:223
	s_waitcnt lgkmcnt(0)
	v_cvt_pk_bf16_f32 v231, v232, v233
	v_lshl_add_u64 v[232:233], v[226:227], 0, v[202:203]
	global_store_dwordx4 v[232:233], v[228:231], off sc1
	ds_read2_b32 v[228:229], v131 offset0:32 offset1:97
	v_mov_b32_e32 v205, v1
	s_waitcnt lgkmcnt(0)
	v_cvt_pk_bf16_f32 v228, v228, v229
	ds_read2_b32 v[230:231], v131 offset0:162 offset1:227
	s_waitcnt lgkmcnt(0)
	v_cvt_pk_bf16_f32 v229, v230, v231
	ds_read2_b32 v[230:231], v165 offset0:36 offset1:101
	s_waitcnt lgkmcnt(0)
	v_cvt_pk_bf16_f32 v230, v230, v231
	ds_read2_b32 v[232:233], v165 offset0:166 offset1:231
	s_waitcnt lgkmcnt(0)
	v_cvt_pk_bf16_f32 v231, v232, v233
	v_lshl_add_u64 v[232:233], v[226:227], 0, v[204:205]
	global_store_dwordx4 v[232:233], v[228:231], off sc1
	ds_read2_b32 v[228:229], v131 offset0:40 offset1:105
	v_mov_b32_e32 v207, v1
	s_waitcnt lgkmcnt(0)
	v_cvt_pk_bf16_f32 v228, v228, v229
	ds_read2_b32 v[230:231], v131 offset0:170 offset1:235
	s_waitcnt lgkmcnt(0)
	v_cvt_pk_bf16_f32 v229, v230, v231
	ds_read2_b32 v[230:231], v165 offset0:44 offset1:109
	s_waitcnt lgkmcnt(0)
	v_cvt_pk_bf16_f32 v230, v230, v231
	ds_read2_b32 v[232:233], v165 offset0:174 offset1:239
	s_waitcnt lgkmcnt(0)
	v_cvt_pk_bf16_f32 v231, v232, v233
	v_lshl_add_u64 v[232:233], v[226:227], 0, v[206:207]
	global_store_dwordx4 v[232:233], v[228:231], off sc1
	ds_read2_b32 v[228:229], v131 offset0:48 offset1:113
	v_mov_b32_e32 v209, v1
	s_waitcnt lgkmcnt(0)
	v_cvt_pk_bf16_f32 v228, v228, v229
	ds_read2_b32 v[230:231], v131 offset0:178 offset1:243
	s_waitcnt lgkmcnt(0)
	v_cvt_pk_bf16_f32 v229, v230, v231
	ds_read2_b32 v[230:231], v165 offset0:52 offset1:117
	s_waitcnt lgkmcnt(0)
	v_cvt_pk_bf16_f32 v230, v230, v231
	ds_read2_b32 v[232:233], v165 offset0:182 offset1:247
	s_waitcnt lgkmcnt(0)
	v_cvt_pk_bf16_f32 v231, v232, v233
	v_lshl_add_u64 v[232:233], v[226:227], 0, v[208:209]
	global_store_dwordx4 v[232:233], v[228:231], off sc1
	ds_read2_b32 v[228:229], v131 offset0:56 offset1:121
	v_mov_b32_e32 v225, v1
	s_waitcnt lgkmcnt(0)
	v_cvt_pk_bf16_f32 v228, v228, v229
	ds_read2_b32 v[230:231], v131 offset0:186 offset1:251
	s_waitcnt lgkmcnt(0)
	v_cvt_pk_bf16_f32 v229, v230, v231
	ds_read2_b32 v[230:231], v165 offset0:60 offset1:125
	v_lshl_add_u64 v[226:227], v[226:227], 0, v[224:225]
	s_waitcnt lgkmcnt(0)
	v_cvt_pk_bf16_f32 v230, v230, v231
	ds_read2_b32 v[232:233], v165 offset0:190 offset1:255
	s_waitcnt lgkmcnt(0)
	v_cvt_pk_bf16_f32 v231, v232, v233
	global_store_dwordx4 v[226:227], v[228:231], off sc1
	s_waitcnt lgkmcnt(0)
	s_andn2_b64 vcc, exec, s[42:43]
	s_cbranch_vccnz .LBB0_381
	v_mov_b64_e32 v[62:63], v[126:127]
	v_mov_b64_e32 v[54:55], v[118:119]
	v_mov_b64_e32 v[58:59], v[122:123]
	v_mov_b64_e32 v[46:47], v[110:111]
	v_mov_b64_e32 v[50:51], v[114:115]
	v_mov_b64_e32 v[38:39], v[102:103]
	v_mov_b64_e32 v[42:43], v[106:107]
	v_mov_b64_e32 v[30:31], v[94:95]
	v_mov_b64_e32 v[34:35], v[98:99]
	v_mov_b64_e32 v[22:23], v[86:87]
	v_mov_b64_e32 v[26:27], v[90:91]
	v_mov_b64_e32 v[14:15], v[78:79]
	v_mov_b64_e32 v[18:19], v[82:83]
	v_mov_b64_e32 v[6:7], v[70:71]
	v_mov_b64_e32 v[10:11], v[74:75]
	v_mov_b64_e32 v[2:3], v[66:67]
	v_mov_b64_e32 v[64:65], v[128:129]
	v_mov_b64_e32 v[56:57], v[120:121]
	v_mov_b64_e32 v[60:61], v[124:125]
	v_mov_b64_e32 v[48:49], v[112:113]
	v_mov_b64_e32 v[52:53], v[116:117]
	v_mov_b64_e32 v[40:41], v[104:105]
	v_mov_b64_e32 v[44:45], v[108:109]
	v_mov_b64_e32 v[32:33], v[96:97]
	v_mov_b64_e32 v[36:37], v[100:101]
	v_mov_b64_e32 v[24:25], v[88:89]
	v_mov_b64_e32 v[28:29], v[92:93]
	v_mov_b64_e32 v[16:17], v[80:81]
	v_mov_b64_e32 v[20:21], v[84:85]
	v_mov_b64_e32 v[8:9], v[72:73]
	v_mov_b64_e32 v[12:13], v[76:77]
	v_mov_b64_e32 v[4:5], v[68:69]
	v_mov_b32_e32 v160, v153
	v_mov_b32_e32 v158, v155
	v_mov_b32_e32 v156, v157
	v_mov_b32_e32 v154, v159
	v_mov_b32_e32 v152, v161
	v_mov_b32_e32 v150, v163
	v_mov_b32_e32 v148, v167
	v_mov_b32_e32 v146, v169
	v_mov_b32_e32 v144, v137
	v_mov_b32_e32 v142, v139
	v_mov_b32_e32 v140, v141
	v_mov_b32_e32 v138, v143
	v_mov_b32_e32 v136, v145
	v_mov_b32_e32 v134, v147
	v_mov_b32_e32 v132, v149
	v_mov_b32_e32 v130, v151
	s_mov_b64 s[28:29], s[44:45]
	s_mov_b32 s7, s4
	s_branch .LBB0_381
.LBB0_386:
	s_waitcnt vmcnt(0)
	s_barrier
	s_mov_b64 s[28:29], exec
	v_readlane_b32 s4, v254, 7
	v_readlane_b32 s5, v254, 8
	s_nop 1
	s_and_b64 exec, s[28:29], s[4:5]
	s_cbranch_execz .Lconv_sig_done
	v_readlane_b32 s6, v252, 34
	v_readlane_b32 s7, v252, 35
	v_mov_b32_e32 v0, 1
	s_nop 3
	global_atomic_add v1, v0, s[6:7] offset:-256
.Lconv_sig_done:
	s_mov_b64 exec, s[28:29]

; __device__ __forceinline__ unsigned xb_add(unsigned* p, unsigned v) { return __hip_atomic_fetch_add(p, v, __ATOMIC_RELAXED, __HIP_MEMORY_SCOPE_AGENT); }
; __device__ __forceinline__ void xcd_barrier(const XcdBarrier& b) {
;     asm volatile("s_waitcnt vmcnt(0)" ::: "memory");
;     __syncthreads();
;     if (threadIdx.x == 0) {
;         unsigned* bar = b.bar;
;         __builtin_amdgcn_s_waitcnt(0);
;         unsigned nloc = b.st[0], nx = b.st[1];
;         if (nloc == 0u) { xcd_barrier_complete(bar, b.x, nloc, nx); b.st[0] = nloc; b.st[1] = nx; }
;         const unsigned old = xb_add(&bar[XB_XSUB(b.x)], 1u);
;         const unsigned gen = old / nloc;
;         if (old + 1u == (gen + 1u) * nloc) {
;             __builtin_amdgcn_fence(__ATOMIC_RELEASE, "agent");
.LBB0_404:
	v_readlane_b32 s6, v252, 34
	v_readlane_b32 s7, v252, 35
	v_mov_b32_e32 v15, 0x23080
	v_mov_b32_e32 v17, 0x80
	ds_add_rtn_u32 v17, v15, v17
	s_nop 2
	global_load_dword v16, v1, s[6:7] offset:-256 sc1
	s_mov_b64 s[42:43], exec
	v_mbcnt_lo_u32_b32 v0, s42, 0
	v_mbcnt_hi_u32_b32 v0, s43, v0
	v_cmp_eq_u32_e32 vcc, 0, v0
	s_and_saveexec_b64 s[30:31], vcc
	s_cbranch_execz .LBB0_406
	s_bcnt1_i32_b64 s5, s[42:43]
	v_readlane_b32 s6, v253, 44
	v_mov_b32_e32 v4, s5
	v_readlane_b32 s7, v253, 45
	s_nop 4
	global_atomic_add v4, v1, v4, s[6:7] sc0
.LBB0_406:
	s_or_b64 exec, exec, s[30:31]
	v_cvt_f32_u32_e32 v5, v3
	s_waitcnt vmcnt(0)
	s_waitcnt lgkmcnt(0)
	v_add_u32_e32 v17, 0x80, v17
	v_readlane_b32 s5, v252, 0
	s_nop 3
	s_cmp_eq_u32 s5, 0
	s_cbranch_scc1 .Lgu_conv_ok
.Lgu_conv_wait:
	v_cmp_ge_u32_e32 vcc, v16, v17
	s_cbranch_vccnz .Lgu_conv_ok
	s_sleep 4
	v_readlane_b32 s6, v252, 34
	v_readlane_b32 s7, v252, 35
	s_nop 4
	global_load_dword v16, v1, s[6:7] offset:-256 sc1
	s_waitcnt vmcnt(0)
	s_branch .Lgu_conv_wait
.Lgu_conv_ok:
	v_readfirstlane_b32 s5, v4
	v_sub_u32_e32 v4, 0, v3
	v_rcp_iflag_f32_e32 v5, v5
	v_add_u32_e32 v6, s5, v0
	v_mul_f32_e32 v5, 0x4f7ffffe, v5
	v_cvt_u32_f32_e32 v5, v5
	v_mul_lo_u32 v0, v4, v5
	v_mul_hi_u32 v0, v5, v0
	v_add_u32_e32 v0, v5, v0
	v_mul_hi_u32 v0, v6, v0
	v_mul_lo_u32 v4, v0, v3
	v_sub_u32_e32 v4, v6, v4
	v_add_u32_e32 v5, 1, v0
	v_cmp_ge_u32_e32 vcc, v4, v3
	s_nop 1
	v_cndmask_b32_e32 v0, v0, v5, vcc
	v_sub_u32_e32 v5, v4, v3
	v_cndmask_b32_e32 v4, v4, v5, vcc
	v_add_u32_e32 v5, 1, v0
	v_cmp_ge_u32_e32 vcc, v4, v3
	v_add_u32_e32 v4, 1, v6
	s_nop 0
	v_cndmask_b32_e32 v0, v0, v5, vcc
	v_mul_lo_u32 v5, v3, v0
	v_add_u32_e32 v3, v5, v3
	v_cmp_ne_u32_e32 vcc, v4, v3
	s_and_saveexec_b64 s[6:7], vcc
	s_xor_b64 s[30:31], exec, s[6:7]
	s_cbranch_execz .LBB0_420
	v_readlane_b32 s6, v252, 49
	v_readlane_b32 s7, v252, 50
	s_waitcnt lgkmcnt(0)
	s_nop 3
	global_load_dword v2, v1, s[6:7] sc1
	s_waitcnt vmcnt(0)
	v_cmp_eq_u32_e32 vcc, v2, v0
	s_and_saveexec_b64 s[42:43], vcc
	s_cbranch_execz .LBB0_419
	s_mov_b32 s5, 1
	s_mov_b64 s[44:45], 0
	s_branch .LBB0_410

; __device__ __forceinline__ unsigned xb_ld(unsigned* p)              { return __hip_atomic_load(p, __ATOMIC_RELAXED, __HIP_MEMORY_SCOPE_AGENT); }
; __device__ __forceinline__ unsigned xb_add(unsigned* p, unsigned v) { return __hip_atomic_fetch_add(p, v, __ATOMIC_RELAXED, __HIP_MEMORY_SCOPE_AGENT); }
; #define XB_SPIN(cond, bar) do { unsigned _sp = 0; while (cond) { __builtin_amdgcn_s_sleep(8); \
;     if ((++_sp & 255u) == 0u) { if (xb_ld(&(bar)[XB_TMO])) break; if (_sp > XB_SPIN_CAP) { atomicAdd(&(bar)[XB_TMO], 1u); break; } } } } while (0)
; __device__ __forceinline__ void xcd_barrier(const XcdBarrier& b) {
;     ...
;         if (old + 1u == (gen + 1u) * nloc) {
;             __builtin_amdgcn_fence(__ATOMIC_RELEASE, "agent");
;             asm volatile("s_waitcnt vmcnt(0)" ::: "memory");
;             const unsigned og = xb_add(&bar[XB_TOP], 1u);
;             const unsigned tg = og / nx;
;             if (og + 1u == (tg + 1u) * nx) xb_add(&bar[XB_TOPGEN], 1u);
;             else XB_SPIN(xb_ld(&bar[XB_TOPGEN]) == tg, bar);
.LBB0_420:
	s_andn2_saveexec_b64 s[6:7], s[30:31]
	s_cbranch_execz .LBB0_442
	s_mov_b64 s[30:31], exec
	v_readlane_b32 s5, v252, 0
	s_nop 3
	s_cmp_lg_u32 s5, 0
	s_cbranch_scc1 .LBB0_439
	buffer_wbl2 sc1
	s_waitcnt lgkmcnt(0)
	s_waitcnt vmcnt(0)
	v_mbcnt_lo_u32_b32 v0, s30, 0
	v_mbcnt_hi_u32_b32 v0, s31, v0
	v_cmp_eq_u32_e32 vcc, 0, v0
	s_and_saveexec_b64 s[42:43], vcc
	s_cbranch_execz .LBB0_423
	s_bcnt1_i32_b64 s5, s[30:31]
	v_readlane_b32 s6, v253, 46
	v_mov_b32_e32 v3, s5
	v_readlane_b32 s7, v253, 47
	s_nop 4
	global_atomic_add v3, v1, v3, s[6:7] sc0

; __device__ __forceinline__ unsigned xb_ld(unsigned* p)              { return __hip_atomic_load(p, __ATOMIC_RELAXED, __HIP_MEMORY_SCOPE_AGENT); }
; __device__ __forceinline__ unsigned xb_add(unsigned* p, unsigned v) { return __hip_atomic_fetch_add(p, v, __ATOMIC_RELAXED, __HIP_MEMORY_SCOPE_AGENT); }
; #define XB_SPIN(cond, bar) do { unsigned _sp = 0; while (cond) { __builtin_amdgcn_s_sleep(8); \
;     if ((++_sp & 255u) == 0u) { if (xb_ld(&(bar)[XB_TMO])) break; if (_sp > XB_SPIN_CAP) { atomicAdd(&(bar)[XB_TMO], 1u); break; } } } } while (0)
; __device__ __forceinline__ void xcd_barrier(const XcdBarrier& b) {
;     ...
;         if (old + 1u == (gen + 1u) * nloc) {
;             __builtin_amdgcn_fence(__ATOMIC_RELEASE, "agent");
;             asm volatile("s_waitcnt vmcnt(0)" ::: "memory");
;             const unsigned og = xb_add(&bar[XB_TOP], 1u);
;             const unsigned tg = og / nx;
;             if (og + 1u == (tg + 1u) * nx) xb_add(&bar[XB_TOPGEN], 1u);
;             else XB_SPIN(xb_ld(&bar[XB_TOPGEN]) == tg, bar);
.LBB0_518:
	s_andn2_saveexec_b64 s[4:5], s[42:43]
	s_cbranch_execz .LBB0_538
	s_mov_b64 s[42:43], exec
	v_readlane_b32 s4, v252, 23
	v_readlane_b32 s5, v252, 0
	s_nop 3
	s_and_b32 s4, s4, s5
	s_cmp_lg_u32 s4, 0
	s_cbranch_scc1 .LBB0_535
	buffer_wbl2 sc1
	s_waitcnt lgkmcnt(0)
	s_waitcnt vmcnt(0)
	v_mbcnt_lo_u32_b32 v0, s42, 0
	v_mbcnt_hi_u32_b32 v0, s43, v0
	v_cmp_eq_u32_e32 vcc, 0, v0
	s_and_saveexec_b64 s[44:45], vcc
	s_cbranch_execz .LBB0_521
	s_bcnt1_i32_b64 s4, s[42:43]
	v_mov_b32_e32 v3, s4
	v_readlane_b32 s4, v253, 46
	v_readlane_b32 s5, v253, 47
	s_nop 4
	global_atomic_add v3, v1, v3, s[4:5] sc0

; __device__ __forceinline__ unsigned xb_ld(unsigned* p)              { return __hip_atomic_load(p, __ATOMIC_RELAXED, __HIP_MEMORY_SCOPE_AGENT); }
; __device__ __forceinline__ unsigned xb_add(unsigned* p, unsigned v) { return __hip_atomic_fetch_add(p, v, __ATOMIC_RELAXED, __HIP_MEMORY_SCOPE_AGENT); }
; #define XB_SPIN(cond, bar) do { unsigned _sp = 0; while (cond) { __builtin_amdgcn_s_sleep(8); \
;     if ((++_sp & 255u) == 0u) { if (xb_ld(&(bar)[XB_TMO])) break; if (_sp > XB_SPIN_CAP) { atomicAdd(&(bar)[XB_TMO], 1u); break; } } } } while (0)
; __device__ __forceinline__ void xcd_barrier(const XcdBarrier& b) {
;     ...
;         if (old + 1u == (gen + 1u) * nloc) {
;             __builtin_amdgcn_fence(__ATOMIC_RELEASE, "agent");
;             asm volatile("s_waitcnt vmcnt(0)" ::: "memory");
;             const unsigned og = xb_add(&bar[XB_TOP], 1u);
;             const unsigned tg = og / nx;
;             if (og + 1u == (tg + 1u) * nx) xb_add(&bar[XB_TOPGEN], 1u);
;             else XB_SPIN(xb_ld(&bar[XB_TOPGEN]) == tg, bar);
.LBB0_1258:
	s_mov_b64 s[30:31], exec
	v_readlane_b32 s4, v252, 0
	s_nop 3
	s_cmp_lg_u32 s4, 0
	s_cbranch_scc1 .LBB0_1274
	buffer_wbl2 sc1
	s_waitcnt lgkmcnt(0)
	s_waitcnt vmcnt(0)
	v_mbcnt_lo_u32_b32 v0, s30, 0
	v_mbcnt_hi_u32_b32 v0, s31, v0
	v_cmp_eq_u32_e32 vcc, 0, v0
	s_and_saveexec_b64 s[42:43], vcc
	s_cbranch_execz .LBB0_1260
	s_bcnt1_i32_b64 s4, s[30:31]
	v_mov_b32_e32 v3, s4
	v_readlane_b32 s4, v253, 46
	v_readlane_b32 s5, v253, 47
	s_nop 4
	global_atomic_add v3, v1, v3, s[4:5] sc0
